# GEMM K-loops: all per-segment s_setprio flips removed (no wave priority changes); on top of all-to-all release
# speedup vs baseline: 1.0109x; 1.0109x over previous
.LBB0_295:
	s_add_u32 s2, s0, 0xfff80080
	s_addc_u32 s3, s1, -1
	s_add_i32 s54, 0, 0x10000
	s_cmp_eq_u32 s53, 28
	s_cselect_b32 s5, s17, s3
	s_cselect_b32 s4, s25, s2
	v_add_u32_e32 v66, s54, v220
	s_cselect_b32 s3, s15, s52
	s_cselect_b32 s2, s28, s51
	s_add_i32 s56, 0, 0x14000
	ds_read_b128 v[132:135], v66
	ds_read_b128 v[136:139], v66 offset:1024
	ds_read_b128 v[140:143], v66 offset:2048
	ds_read_b128 v[144:147], v66 offset:3072
	v_add_u32_e32 v66, s56, v220
	ds_read_b128 v[148:151], v66
	ds_read_b128 v[152:155], v66 offset:1024
	ds_read_b128 v[156:159], v66 offset:2048
	ds_read_b128 v[160:163], v66 offset:3072
	v_lshl_add_u64 v[204:205], s[0:1], 0, v[180:181]
	s_add_i32 m0, s9, 0xc000
	ds_read_b128 v[184:187], v222
	ds_read_b128 v[188:191], v222 offset:1024
	ds_read_b128 v[192:195], v222 offset:2048
	ds_read_b128 v[196:199], v222 offset:3072
	ds_read_b128 v[200:203], v222 offset:4096
	ds_read_b128 v[224:227], v222 offset:5120
	ds_read_b128 v[228:231], v222 offset:6144
	ds_read_b128 v[232:235], v222 offset:7168
	global_load_lds_dwordx4 v[204:205], off
	v_lshl_add_u64 v[204:205], s[0:1], 0, v[182:183]
	s_add_i32 m0, s9, 0xe000
	s_nop 0
	global_load_lds_dwordx4 v[204:205], off
	s_waitcnt vmcnt(8)
	s_waitcnt lgkmcnt(0)
	s_barrier
	s_waitcnt lgkmcnt(0)
	v_mfma_f32_16x16x32_bf16 v[128:131], v[132:135], v[184:187], v[128:131]
	v_mfma_f32_16x16x32_bf16 v[124:127], v[140:143], v[184:187], v[124:127]
	v_mfma_f32_16x16x32_bf16 v[120:123], v[132:135], v[192:195], v[120:123]
	v_mfma_f32_16x16x32_bf16 v[116:119], v[140:143], v[192:195], v[116:119]
	v_mfma_f32_16x16x32_bf16 v[112:115], v[132:135], v[200:203], v[112:115]
	v_mfma_f32_16x16x32_bf16 v[104:107], v[140:143], v[200:203], v[104:107]
	v_mfma_f32_16x16x32_bf16 v[96:99], v[132:135], v[228:231], v[96:99]
	v_mfma_f32_16x16x32_bf16 v[88:91], v[140:143], v[228:231], v[88:91]
	v_mfma_f32_16x16x32_bf16 v[128:131], v[136:139], v[188:191], v[128:131]
	v_mfma_f32_16x16x32_bf16 v[124:127], v[144:147], v[188:191], v[124:127]
	v_mfma_f32_16x16x32_bf16 v[120:123], v[136:139], v[196:199], v[120:123]
	v_mfma_f32_16x16x32_bf16 v[116:119], v[144:147], v[196:199], v[116:119]
	v_mfma_f32_16x16x32_bf16 v[112:115], v[136:139], v[224:227], v[112:115]
	v_mfma_f32_16x16x32_bf16 v[104:107], v[144:147], v[224:227], v[104:107]
	v_mfma_f32_16x16x32_bf16 v[96:99], v[136:139], v[232:235], v[96:99]
	v_mfma_f32_16x16x32_bf16 v[88:91], v[144:147], v[232:235], v[88:91]
	v_mfma_f32_16x16x32_bf16 v[108:111], v[148:151], v[184:187], v[108:111]
	v_mfma_f32_16x16x32_bf16 v[100:103], v[156:159], v[184:187], v[100:103]
	v_mfma_f32_16x16x32_bf16 v[92:95], v[148:151], v[192:195], v[92:95]
	v_mfma_f32_16x16x32_bf16 v[84:87], v[156:159], v[192:195], v[84:87]
	v_mfma_f32_16x16x32_bf16 v[80:83], v[148:151], v[200:203], v[80:83]
	v_mfma_f32_16x16x32_bf16 v[76:79], v[156:159], v[200:203], v[76:79]
	v_mfma_f32_16x16x32_bf16 v[72:75], v[148:151], v[228:231], v[72:75]
	v_mfma_f32_16x16x32_bf16 v[68:71], v[156:159], v[228:231], v[68:71]
	v_mfma_f32_16x16x32_bf16 v[108:111], v[152:155], v[188:191], v[108:111]
	v_mfma_f32_16x16x32_bf16 v[100:103], v[160:163], v[188:191], v[100:103]
	v_mfma_f32_16x16x32_bf16 v[92:95], v[152:155], v[196:199], v[92:95]
	v_mfma_f32_16x16x32_bf16 v[84:87], v[160:163], v[196:199], v[84:87]
	v_mfma_f32_16x16x32_bf16 v[80:83], v[152:155], v[224:227], v[80:83]
	v_mfma_f32_16x16x32_bf16 v[76:79], v[160:163], v[224:227], v[76:79]
	v_mfma_f32_16x16x32_bf16 v[72:75], v[152:155], v[232:235], v[72:75]
	v_mfma_f32_16x16x32_bf16 v[68:71], v[160:163], v[232:235], v[68:71]
	s_barrier
	s_add_i32 s54, s54, s40
	v_lshl_add_u64 v[204:205], s[2:3], 0, v[170:171]
	s_mov_b32 m0, s54
	ds_read_b128 v[184:187], v222 offset:16384
	ds_read_b128 v[188:191], v222 offset:17408
	ds_read_b128 v[192:195], v222 offset:18432
	ds_read_b128 v[196:199], v222 offset:19456
	ds_read_b128 v[200:203], v222 offset:20480
	ds_read_b128 v[224:227], v222 offset:21504
	ds_read_b128 v[228:231], v222 offset:22528
	ds_read_b128 v[232:235], v222 offset:23552
	global_load_lds_dwordx4 v[204:205], off
	s_add_i32 m0, s54, 0x2000
	s_add_u32 s54, s2, 0x80000
	v_lshl_add_u64 v[236:237], s[2:3], 0, v[174:175]
	s_addc_u32 s55, s3, 0
	s_add_i32 s56, s56, s40
	global_load_lds_dwordx4 v[236:237], off
	v_lshl_add_u64 v[238:239], s[54:55], 0, v[170:171]
	s_mov_b32 m0, s56
	v_lshl_add_u64 v[240:241], s[4:5], 0, v[172:173]
	global_load_lds_dwordx4 v[238:239], off
	v_lshl_add_u64 v[238:239], s[54:55], 0, v[174:175]
	s_add_i32 m0, s56, 0x2000
	s_nop 0
	global_load_lds_dwordx4 v[238:239], off
	v_lshl_add_u64 v[238:239], s[4:5], 0, v[168:169]
	s_mov_b32 m0, s9
	s_nop 0
	global_load_lds_dwordx4 v[238:239], off
	s_mov_b32 m0, s39
	s_nop 0
	global_load_lds_dwordx4 v[240:241], off
	s_waitcnt vmcnt(8)
	s_waitcnt lgkmcnt(0)
	s_barrier
	s_waitcnt lgkmcnt(0)
	v_mfma_f32_16x16x32_bf16 v[62:65], v[132:135], v[184:187], v[62:65]
	v_mfma_f32_16x16x32_bf16 v[58:61], v[140:143], v[184:187], v[58:61]
	v_mfma_f32_16x16x32_bf16 v[54:57], v[132:135], v[192:195], v[54:57]
	v_mfma_f32_16x16x32_bf16 v[50:53], v[140:143], v[192:195], v[50:53]
	v_mfma_f32_16x16x32_bf16 v[46:49], v[132:135], v[200:203], v[46:49]
	v_mfma_f32_16x16x32_bf16 v[38:41], v[140:143], v[200:203], v[38:41]
	v_mfma_f32_16x16x32_bf16 v[30:33], v[132:135], v[228:231], v[30:33]
	v_mfma_f32_16x16x32_bf16 v[22:25], v[140:143], v[228:231], v[22:25]
	v_mfma_f32_16x16x32_bf16 v[62:65], v[136:139], v[188:191], v[62:65]
	v_mfma_f32_16x16x32_bf16 v[58:61], v[144:147], v[188:191], v[58:61]
	v_mfma_f32_16x16x32_bf16 v[54:57], v[136:139], v[196:199], v[54:57]
	v_mfma_f32_16x16x32_bf16 v[50:53], v[144:147], v[196:199], v[50:53]
	v_mfma_f32_16x16x32_bf16 v[46:49], v[136:139], v[224:227], v[46:49]
	v_mfma_f32_16x16x32_bf16 v[38:41], v[144:147], v[224:227], v[38:41]
	v_mfma_f32_16x16x32_bf16 v[30:33], v[136:139], v[232:235], v[30:33]
	v_mfma_f32_16x16x32_bf16 v[22:25], v[144:147], v[232:235], v[22:25]
	v_mfma_f32_16x16x32_bf16 v[42:45], v[148:151], v[184:187], v[42:45]
	v_mfma_f32_16x16x32_bf16 v[34:37], v[156:159], v[184:187], v[34:37]
	v_mfma_f32_16x16x32_bf16 v[26:29], v[148:151], v[192:195], v[26:29]
	v_mfma_f32_16x16x32_bf16 v[18:21], v[156:159], v[192:195], v[18:21]
	v_mfma_f32_16x16x32_bf16 v[14:17], v[148:151], v[200:203], v[14:17]
	v_mfma_f32_16x16x32_bf16 v[10:13], v[156:159], v[200:203], v[10:13]
	v_mfma_f32_16x16x32_bf16 v[6:9], v[148:151], v[228:231], v[6:9]
	v_mfma_f32_16x16x32_bf16 v[2:5], v[156:159], v[228:231], v[2:5]
	v_mfma_f32_16x16x32_bf16 v[42:45], v[152:155], v[188:191], v[42:45]
	v_mfma_f32_16x16x32_bf16 v[34:37], v[160:163], v[188:191], v[34:37]
	v_mfma_f32_16x16x32_bf16 v[26:29], v[152:155], v[196:199], v[26:29]
	v_mfma_f32_16x16x32_bf16 v[18:21], v[160:163], v[196:199], v[18:21]
	v_mfma_f32_16x16x32_bf16 v[14:17], v[152:155], v[224:227], v[14:17]
	v_mfma_f32_16x16x32_bf16 v[10:13], v[160:163], v[224:227], v[10:13]
	v_mfma_f32_16x16x32_bf16 v[6:9], v[152:155], v[232:235], v[6:9]
	v_mfma_f32_16x16x32_bf16 v[2:5], v[160:163], v[232:235], v[2:5]
	s_barrier
	s_add_i32 s54, 0, 0x18000
	v_add_u32_e32 v66, s54, v220
	s_add_i32 s55, 0, 0x1c000
	ds_read_b128 v[132:135], v66
	ds_read_b128 v[136:139], v66 offset:1024
	ds_read_b128 v[140:143], v66 offset:2048
	ds_read_b128 v[144:147], v66 offset:3072
	v_add_u32_e32 v66, s55, v220
	ds_read_b128 v[148:151], v66
	ds_read_b128 v[152:155], v66 offset:1024
	ds_read_b128 v[156:159], v66 offset:2048
	ds_read_b128 v[160:163], v66 offset:3072
	s_add_u32 s4, s4, 0x80000
	s_addc_u32 s5, s5, 0
	s_mov_b32 m0, s41
	v_lshl_add_u64 v[242:243], s[4:5], 0, v[168:169]
	ds_read_b128 v[184:187], v222 offset:32768
	ds_read_b128 v[188:191], v222 offset:33792
	ds_read_b128 v[192:195], v222 offset:34816
	ds_read_b128 v[196:199], v222 offset:35840
	ds_read_b128 v[200:203], v222 offset:36864
	ds_read_b128 v[224:227], v222 offset:37888
	ds_read_b128 v[228:231], v222 offset:38912
	ds_read_b128 v[232:235], v222 offset:39936
	global_load_lds_dwordx4 v[242:243], off
	v_lshl_add_u64 v[242:243], s[4:5], 0, v[172:173]
	s_mov_b32 m0, s42
	s_nop 0
	global_load_lds_dwordx4 v[242:243], off
	s_waitcnt vmcnt(8)
	s_waitcnt lgkmcnt(0)
	s_barrier
	s_waitcnt lgkmcnt(0)
	v_mfma_f32_16x16x32_bf16 v[128:131], v[132:135], v[184:187], v[128:131]
	v_mfma_f32_16x16x32_bf16 v[124:127], v[140:143], v[184:187], v[124:127]
	v_mfma_f32_16x16x32_bf16 v[120:123], v[132:135], v[192:195], v[120:123]
	v_mfma_f32_16x16x32_bf16 v[116:119], v[140:143], v[192:195], v[116:119]
	v_mfma_f32_16x16x32_bf16 v[112:115], v[132:135], v[200:203], v[112:115]
	v_mfma_f32_16x16x32_bf16 v[104:107], v[140:143], v[200:203], v[104:107]
	v_mfma_f32_16x16x32_bf16 v[96:99], v[132:135], v[228:231], v[96:99]
	v_mfma_f32_16x16x32_bf16 v[88:91], v[140:143], v[228:231], v[88:91]
	v_mfma_f32_16x16x32_bf16 v[128:131], v[136:139], v[188:191], v[128:131]
	v_mfma_f32_16x16x32_bf16 v[124:127], v[144:147], v[188:191], v[124:127]
	v_mfma_f32_16x16x32_bf16 v[120:123], v[136:139], v[196:199], v[120:123]
	v_mfma_f32_16x16x32_bf16 v[116:119], v[144:147], v[196:199], v[116:119]
	v_mfma_f32_16x16x32_bf16 v[112:115], v[136:139], v[224:227], v[112:115]
	v_mfma_f32_16x16x32_bf16 v[104:107], v[144:147], v[224:227], v[104:107]
	v_mfma_f32_16x16x32_bf16 v[96:99], v[136:139], v[232:235], v[96:99]
	v_mfma_f32_16x16x32_bf16 v[88:91], v[144:147], v[232:235], v[88:91]
	v_mfma_f32_16x16x32_bf16 v[108:111], v[148:151], v[184:187], v[108:111]
	v_mfma_f32_16x16x32_bf16 v[100:103], v[156:159], v[184:187], v[100:103]
	v_mfma_f32_16x16x32_bf16 v[92:95], v[148:151], v[192:195], v[92:95]
	v_mfma_f32_16x16x32_bf16 v[84:87], v[156:159], v[192:195], v[84:87]
	v_mfma_f32_16x16x32_bf16 v[80:83], v[148:151], v[200:203], v[80:83]
	v_mfma_f32_16x16x32_bf16 v[76:79], v[156:159], v[200:203], v[76:79]
	v_mfma_f32_16x16x32_bf16 v[72:75], v[148:151], v[228:231], v[72:75]
	v_mfma_f32_16x16x32_bf16 v[68:71], v[156:159], v[228:231], v[68:71]
	v_mfma_f32_16x16x32_bf16 v[108:111], v[152:155], v[188:191], v[108:111]
	v_mfma_f32_16x16x32_bf16 v[100:103], v[160:163], v[188:191], v[100:103]
	v_mfma_f32_16x16x32_bf16 v[92:95], v[152:155], v[196:199], v[92:95]
	v_mfma_f32_16x16x32_bf16 v[84:87], v[160:163], v[196:199], v[84:87]
	v_mfma_f32_16x16x32_bf16 v[80:83], v[152:155], v[224:227], v[80:83]
	v_mfma_f32_16x16x32_bf16 v[76:79], v[160:163], v[224:227], v[76:79]
	v_mfma_f32_16x16x32_bf16 v[72:75], v[152:155], v[232:235], v[72:75]
	v_mfma_f32_16x16x32_bf16 v[68:71], v[160:163], v[232:235], v[68:71]
	s_barrier
	s_add_i32 s4, s54, s40
	v_lshl_add_u64 v[204:205], v[204:205], 0, s[58:59]
	s_mov_b32 m0, s4
	ds_read_b128 v[184:187], v222 offset:49152
	ds_read_b128 v[188:191], v222 offset:50176
	ds_read_b128 v[192:195], v222 offset:51200
	ds_read_b128 v[196:199], v222 offset:52224
	ds_read_b128 v[200:203], v222 offset:53248
	ds_read_b128 v[224:227], v222 offset:54272
	ds_read_b128 v[228:231], v222 offset:55296
	ds_read_b128 v[232:235], v222 offset:56320
	global_load_lds_dwordx4 v[204:205], off
	s_add_i32 m0, s4, 0x2000
	s_add_u32 s2, s2, 0x80080
	v_lshl_add_u64 v[204:205], v[236:237], 0, s[58:59]
	s_addc_u32 s3, s3, 0
	s_add_i32 s4, s55, s40
	global_load_lds_dwordx4 v[204:205], off
	v_lshl_add_u64 v[204:205], s[2:3], 0, v[170:171]
	s_mov_b32 m0, s4
	s_nop 0
	global_load_lds_dwordx4 v[204:205], off
	v_lshl_add_u64 v[204:205], s[2:3], 0, v[174:175]
	s_add_i32 m0, s4, 0x2000
	s_nop 0
	global_load_lds_dwordx4 v[204:205], off
	v_lshl_add_u64 v[204:205], v[238:239], 0, s[58:59]
	s_mov_b32 m0, s48
	s_nop 0
	global_load_lds_dwordx4 v[204:205], off
	v_lshl_add_u64 v[204:205], v[240:241], 0, s[58:59]
	s_mov_b32 m0, s49
	s_nop 0
	global_load_lds_dwordx4 v[204:205], off
	s_waitcnt vmcnt(8)
	s_waitcnt lgkmcnt(0)
	s_barrier
	s_waitcnt lgkmcnt(0)
	v_mfma_f32_16x16x32_bf16 v[62:65], v[132:135], v[184:187], v[62:65]
	v_mfma_f32_16x16x32_bf16 v[58:61], v[140:143], v[184:187], v[58:61]
	v_mfma_f32_16x16x32_bf16 v[54:57], v[132:135], v[192:195], v[54:57]
	v_mfma_f32_16x16x32_bf16 v[50:53], v[140:143], v[192:195], v[50:53]
	v_mfma_f32_16x16x32_bf16 v[46:49], v[132:135], v[200:203], v[46:49]
	v_mfma_f32_16x16x32_bf16 v[38:41], v[140:143], v[200:203], v[38:41]
	v_mfma_f32_16x16x32_bf16 v[30:33], v[132:135], v[228:231], v[30:33]
	v_mfma_f32_16x16x32_bf16 v[22:25], v[140:143], v[228:231], v[22:25]
	v_mfma_f32_16x16x32_bf16 v[62:65], v[136:139], v[188:191], v[62:65]
	v_mfma_f32_16x16x32_bf16 v[58:61], v[144:147], v[188:191], v[58:61]
	v_mfma_f32_16x16x32_bf16 v[54:57], v[136:139], v[196:199], v[54:57]
	v_mfma_f32_16x16x32_bf16 v[50:53], v[144:147], v[196:199], v[50:53]
	v_mfma_f32_16x16x32_bf16 v[46:49], v[136:139], v[224:227], v[46:49]
	v_mfma_f32_16x16x32_bf16 v[38:41], v[144:147], v[224:227], v[38:41]
	v_mfma_f32_16x16x32_bf16 v[30:33], v[136:139], v[232:235], v[30:33]
	v_mfma_f32_16x16x32_bf16 v[22:25], v[144:147], v[232:235], v[22:25]
	v_mfma_f32_16x16x32_bf16 v[42:45], v[148:151], v[184:187], v[42:45]
	v_mfma_f32_16x16x32_bf16 v[34:37], v[156:159], v[184:187], v[34:37]
	v_mfma_f32_16x16x32_bf16 v[26:29], v[148:151], v[192:195], v[26:29]
	v_mfma_f32_16x16x32_bf16 v[18:21], v[156:159], v[192:195], v[18:21]
	v_mfma_f32_16x16x32_bf16 v[14:17], v[148:151], v[200:203], v[14:17]
	v_mfma_f32_16x16x32_bf16 v[10:13], v[156:159], v[200:203], v[10:13]
	v_mfma_f32_16x16x32_bf16 v[6:9], v[148:151], v[228:231], v[6:9]
	v_mfma_f32_16x16x32_bf16 v[2:5], v[156:159], v[228:231], v[2:5]
	v_mfma_f32_16x16x32_bf16 v[42:45], v[152:155], v[188:191], v[42:45]
	v_mfma_f32_16x16x32_bf16 v[34:37], v[160:163], v[188:191], v[34:37]
	v_mfma_f32_16x16x32_bf16 v[26:29], v[152:155], v[196:199], v[26:29]
	v_mfma_f32_16x16x32_bf16 v[18:21], v[160:163], v[196:199], v[18:21]
	v_mfma_f32_16x16x32_bf16 v[14:17], v[152:155], v[224:227], v[14:17]
	v_mfma_f32_16x16x32_bf16 v[10:13], v[160:163], v[224:227], v[10:13]
	v_mfma_f32_16x16x32_bf16 v[6:9], v[152:155], v[232:235], v[6:9]
	v_mfma_f32_16x16x32_bf16 v[2:5], v[160:163], v[232:235], v[2:5]
	s_barrier
	s_add_i32 s53, s53, 2
	s_add_u32 s0, s0, 0x100
	s_addc_u32 s1, s1, 0
	s_add_u32 s51, s51, 0x100
	s_addc_u32 s52, s52, 0
	s_cmp_gt_u32 s53, 29
	s_cbranch_scc0 .LBB0_295
	s_and_b64 vcc, exec, s[12:13]
	s_cbranch_vccz .LBB0_298
	s_barrier

.LBB0_1491:
	s_add_u32 s20, s18, 0x100
	s_addc_u32 s21, s19, 0
	s_add_i32 s55, 0, 0x10000
	s_cmp_eq_u32 s54, 28
	s_cselect_b32 s39, s13, s21
	s_cselect_b32 s38, s50, s20
	s_cselect_b32 s23, s11, s53
	s_cselect_b32 s22, s51, s52
	s_add_i32 s56, 0, 0x14000
	v_add_u32_e32 v144, s55, v169
	v_add_u32_e32 v162, s56, v169
	ds_read_b128 v[132:135], v144
	ds_read_b128 v[136:139], v144 offset:1024
	ds_read_b128 v[140:143], v144 offset:2048
	ds_read_b128 v[144:147], v144 offset:3072
	ds_read_b128 v[158:161], v162
	ds_read_b128 v[172:175], v162 offset:1024
	ds_read_b128 v[176:179], v162 offset:2048
	ds_read_b128 v[180:183], v162 offset:3072
	v_lshl_add_u64 v[162:163], s[18:19], 0, v[154:155]
	s_add_i32 m0, s41, 0xc000
	ds_read_b128 v[184:187], v171
	ds_read_b128 v[188:191], v171 offset:1024
	ds_read_b128 v[192:195], v171 offset:2048
	ds_read_b128 v[196:199], v171 offset:3072
	ds_read_b128 v[200:203], v171 offset:4096
	ds_read_b128 v[218:221], v171 offset:5120
	ds_read_b128 v[222:225], v171 offset:6144
	ds_read_b128 v[226:229], v171 offset:7168
	global_load_lds_dwordx4 v[162:163], off
	v_lshl_add_u64 v[162:163], s[18:19], 0, v[156:157]
	s_add_i32 m0, s41, 0xe000
	s_nop 0
	global_load_lds_dwordx4 v[162:163], off
	s_waitcnt vmcnt(8)
	s_waitcnt lgkmcnt(0)
	s_barrier
	s_waitcnt lgkmcnt(0)
	v_mfma_f32_16x16x32_bf16 v[128:131], v[132:135], v[184:187], v[128:131]
	v_mfma_f32_16x16x32_bf16 v[124:127], v[140:143], v[184:187], v[124:127]
	v_mfma_f32_16x16x32_bf16 v[120:123], v[132:135], v[192:195], v[120:123]
	v_mfma_f32_16x16x32_bf16 v[116:119], v[140:143], v[192:195], v[116:119]
	v_mfma_f32_16x16x32_bf16 v[112:115], v[132:135], v[200:203], v[112:115]
	v_mfma_f32_16x16x32_bf16 v[100:103], v[140:143], v[200:203], v[100:103]
	v_mfma_f32_16x16x32_bf16 v[84:87], v[132:135], v[222:225], v[84:87]
	v_mfma_f32_16x16x32_bf16 v[76:79], v[140:143], v[222:225], v[76:79]
	v_mfma_f32_16x16x32_bf16 v[128:131], v[136:139], v[188:191], v[128:131]
	v_mfma_f32_16x16x32_bf16 v[124:127], v[144:147], v[188:191], v[124:127]
	v_mfma_f32_16x16x32_bf16 v[120:123], v[136:139], v[196:199], v[120:123]
	v_mfma_f32_16x16x32_bf16 v[116:119], v[144:147], v[196:199], v[116:119]
	v_mfma_f32_16x16x32_bf16 v[112:115], v[136:139], v[218:221], v[112:115]
	v_mfma_f32_16x16x32_bf16 v[100:103], v[144:147], v[218:221], v[100:103]
	v_mfma_f32_16x16x32_bf16 v[84:87], v[136:139], v[226:229], v[84:87]
	v_mfma_f32_16x16x32_bf16 v[76:79], v[144:147], v[226:229], v[76:79]
	v_mfma_f32_16x16x32_bf16 v[108:111], v[158:161], v[184:187], v[108:111]
	v_mfma_f32_16x16x32_bf16 v[104:107], v[176:179], v[184:187], v[104:107]
	v_mfma_f32_16x16x32_bf16 v[96:99], v[158:161], v[192:195], v[96:99]
	v_mfma_f32_16x16x32_bf16 v[92:95], v[176:179], v[192:195], v[92:95]
	v_mfma_f32_16x16x32_bf16 v[88:91], v[158:161], v[200:203], v[88:91]
	v_mfma_f32_16x16x32_bf16 v[80:83], v[176:179], v[200:203], v[80:83]
	v_mfma_f32_16x16x32_bf16 v[72:75], v[158:161], v[222:225], v[72:75]
	v_mfma_f32_16x16x32_bf16 v[68:71], v[176:179], v[222:225], v[68:71]
	v_mfma_f32_16x16x32_bf16 v[108:111], v[172:175], v[188:191], v[108:111]
	v_mfma_f32_16x16x32_bf16 v[104:107], v[180:183], v[188:191], v[104:107]
	v_mfma_f32_16x16x32_bf16 v[96:99], v[172:175], v[196:199], v[96:99]
	v_mfma_f32_16x16x32_bf16 v[92:95], v[180:183], v[196:199], v[92:95]
	v_mfma_f32_16x16x32_bf16 v[88:91], v[172:175], v[218:221], v[88:91]
	v_mfma_f32_16x16x32_bf16 v[80:83], v[180:183], v[218:221], v[80:83]
	v_mfma_f32_16x16x32_bf16 v[72:75], v[172:175], v[226:229], v[72:75]
	v_mfma_f32_16x16x32_bf16 v[68:71], v[180:183], v[226:229], v[68:71]
	s_barrier
	s_add_i32 s18, s55, s25
	v_lshl_add_u64 v[162:163], s[22:23], 0, v[66:67]
	s_mov_b32 m0, s18
	ds_read_b128 v[184:187], v171 offset:16384
	ds_read_b128 v[188:191], v171 offset:17408
	ds_read_b128 v[192:195], v171 offset:18432
	ds_read_b128 v[196:199], v171 offset:19456
	ds_read_b128 v[200:203], v171 offset:20480
	ds_read_b128 v[218:221], v171 offset:21504
	ds_read_b128 v[222:225], v171 offset:22528
	ds_read_b128 v[226:229], v171 offset:23552
	global_load_lds_dwordx4 v[162:163], off
	s_add_i32 m0, s18, 0x2000
	s_add_u32 s18, s22, 0x80000
	v_lshl_add_u64 v[204:205], s[22:23], 0, v[148:149]
	s_addc_u32 s19, s23, 0
	s_add_i32 s55, s56, s25
	global_load_lds_dwordx4 v[204:205], off
	v_lshl_add_u64 v[230:231], s[18:19], 0, v[66:67]
	s_mov_b32 m0, s55
	v_lshl_add_u64 v[232:233], s[38:39], 0, v[148:149]
	global_load_lds_dwordx4 v[230:231], off
	v_lshl_add_u64 v[230:231], s[18:19], 0, v[148:149]
	s_add_i32 m0, s55, 0x2000
	s_nop 0
	global_load_lds_dwordx4 v[230:231], off
	v_lshl_add_u64 v[230:231], s[38:39], 0, v[66:67]
	s_mov_b32 m0, s41
	s_nop 0
	global_load_lds_dwordx4 v[230:231], off
	s_mov_b32 m0, s42
	s_nop 0
	global_load_lds_dwordx4 v[232:233], off
	s_waitcnt vmcnt(8)
	s_waitcnt lgkmcnt(0)
	s_barrier
	s_waitcnt lgkmcnt(0)
	v_mfma_f32_16x16x32_bf16 v[62:65], v[132:135], v[184:187], v[62:65]
	v_mfma_f32_16x16x32_bf16 v[58:61], v[140:143], v[184:187], v[58:61]
	v_mfma_f32_16x16x32_bf16 v[54:57], v[132:135], v[192:195], v[54:57]
	v_mfma_f32_16x16x32_bf16 v[50:53], v[140:143], v[192:195], v[50:53]
	v_mfma_f32_16x16x32_bf16 v[46:49], v[132:135], v[200:203], v[46:49]
	v_mfma_f32_16x16x32_bf16 v[34:37], v[140:143], v[200:203], v[34:37]
	v_mfma_f32_16x16x32_bf16 v[22:25], v[132:135], v[222:225], v[22:25]
	v_mfma_f32_16x16x32_bf16 v[14:17], v[140:143], v[222:225], v[14:17]
	v_mfma_f32_16x16x32_bf16 v[62:65], v[136:139], v[188:191], v[62:65]
	v_mfma_f32_16x16x32_bf16 v[58:61], v[144:147], v[188:191], v[58:61]
	v_mfma_f32_16x16x32_bf16 v[54:57], v[136:139], v[196:199], v[54:57]
	v_mfma_f32_16x16x32_bf16 v[50:53], v[144:147], v[196:199], v[50:53]
	v_mfma_f32_16x16x32_bf16 v[46:49], v[136:139], v[218:221], v[46:49]
	v_mfma_f32_16x16x32_bf16 v[34:37], v[144:147], v[218:221], v[34:37]
	v_mfma_f32_16x16x32_bf16 v[22:25], v[136:139], v[226:229], v[22:25]
	v_mfma_f32_16x16x32_bf16 v[14:17], v[144:147], v[226:229], v[14:17]
	v_mfma_f32_16x16x32_bf16 v[42:45], v[158:161], v[184:187], v[42:45]
	v_mfma_f32_16x16x32_bf16 v[38:41], v[176:179], v[184:187], v[38:41]
	v_mfma_f32_16x16x32_bf16 v[30:33], v[158:161], v[192:195], v[30:33]
	v_mfma_f32_16x16x32_bf16 v[26:29], v[176:179], v[192:195], v[26:29]
	v_mfma_f32_16x16x32_bf16 v[18:21], v[158:161], v[200:203], v[18:21]
	v_mfma_f32_16x16x32_bf16 v[10:13], v[176:179], v[200:203], v[10:13]
	v_mfma_f32_16x16x32_bf16 v[6:9], v[158:161], v[222:225], v[6:9]
	v_mfma_f32_16x16x32_bf16 v[2:5], v[176:179], v[222:225], v[2:5]
	v_mfma_f32_16x16x32_bf16 v[42:45], v[172:175], v[188:191], v[42:45]
	v_mfma_f32_16x16x32_bf16 v[38:41], v[180:183], v[188:191], v[38:41]
	v_mfma_f32_16x16x32_bf16 v[30:33], v[172:175], v[196:199], v[30:33]
	v_mfma_f32_16x16x32_bf16 v[26:29], v[180:183], v[196:199], v[26:29]
	v_mfma_f32_16x16x32_bf16 v[18:21], v[172:175], v[218:221], v[18:21]
	v_mfma_f32_16x16x32_bf16 v[10:13], v[180:183], v[218:221], v[10:13]
	v_mfma_f32_16x16x32_bf16 v[6:9], v[172:175], v[226:229], v[6:9]
	v_mfma_f32_16x16x32_bf16 v[2:5], v[180:183], v[226:229], v[2:5]
	s_barrier
	s_add_i32 s55, 0, 0x18000
	s_add_i32 s56, 0, 0x1c000
	v_add_u32_e32 v144, s55, v169
	v_add_u32_e32 v164, s56, v169
	ds_read_b128 v[132:135], v144
	ds_read_b128 v[136:139], v144 offset:1024
	ds_read_b128 v[140:143], v144 offset:2048
	ds_read_b128 v[144:147], v144 offset:3072
	ds_read_b128 v[158:161], v164
	ds_read_b128 v[172:175], v164 offset:1024
	ds_read_b128 v[176:179], v164 offset:2048
	ds_read_b128 v[180:183], v164 offset:3072
	s_add_u32 s18, s38, 0x80000
	s_addc_u32 s19, s39, 0
	s_mov_b32 m0, s43
	v_lshl_add_u64 v[234:235], s[18:19], 0, v[66:67]
	ds_read_b128 v[184:187], v171 offset:32768
	ds_read_b128 v[188:191], v171 offset:33792
	ds_read_b128 v[192:195], v171 offset:34816
	ds_read_b128 v[196:199], v171 offset:35840
	ds_read_b128 v[200:203], v171 offset:36864
	ds_read_b128 v[218:221], v171 offset:37888
	ds_read_b128 v[222:225], v171 offset:38912
	ds_read_b128 v[226:229], v171 offset:39936
	global_load_lds_dwordx4 v[234:235], off
	v_lshl_add_u64 v[234:235], s[18:19], 0, v[148:149]
	s_mov_b32 m0, s44
	s_nop 0
	global_load_lds_dwordx4 v[234:235], off
	s_waitcnt vmcnt(8)
	s_waitcnt lgkmcnt(0)
	s_barrier
	s_waitcnt lgkmcnt(0)
	v_mfma_f32_16x16x32_bf16 v[128:131], v[132:135], v[184:187], v[128:131]
	v_mfma_f32_16x16x32_bf16 v[124:127], v[140:143], v[184:187], v[124:127]
	v_mfma_f32_16x16x32_bf16 v[120:123], v[132:135], v[192:195], v[120:123]
	v_mfma_f32_16x16x32_bf16 v[116:119], v[140:143], v[192:195], v[116:119]
	v_mfma_f32_16x16x32_bf16 v[112:115], v[132:135], v[200:203], v[112:115]
	v_mfma_f32_16x16x32_bf16 v[100:103], v[140:143], v[200:203], v[100:103]
	v_mfma_f32_16x16x32_bf16 v[84:87], v[132:135], v[222:225], v[84:87]
	v_mfma_f32_16x16x32_bf16 v[76:79], v[140:143], v[222:225], v[76:79]
	v_mfma_f32_16x16x32_bf16 v[128:131], v[136:139], v[188:191], v[128:131]
	v_mfma_f32_16x16x32_bf16 v[124:127], v[144:147], v[188:191], v[124:127]
	v_mfma_f32_16x16x32_bf16 v[120:123], v[136:139], v[196:199], v[120:123]
	v_mfma_f32_16x16x32_bf16 v[116:119], v[144:147], v[196:199], v[116:119]
	v_mfma_f32_16x16x32_bf16 v[112:115], v[136:139], v[218:221], v[112:115]
	v_mfma_f32_16x16x32_bf16 v[100:103], v[144:147], v[218:221], v[100:103]
	v_mfma_f32_16x16x32_bf16 v[84:87], v[136:139], v[226:229], v[84:87]
	v_mfma_f32_16x16x32_bf16 v[76:79], v[144:147], v[226:229], v[76:79]
	v_mfma_f32_16x16x32_bf16 v[108:111], v[158:161], v[184:187], v[108:111]
	v_mfma_f32_16x16x32_bf16 v[104:107], v[176:179], v[184:187], v[104:107]
	v_mfma_f32_16x16x32_bf16 v[96:99], v[158:161], v[192:195], v[96:99]
	v_mfma_f32_16x16x32_bf16 v[92:95], v[176:179], v[192:195], v[92:95]
	v_mfma_f32_16x16x32_bf16 v[88:91], v[158:161], v[200:203], v[88:91]
	v_mfma_f32_16x16x32_bf16 v[80:83], v[176:179], v[200:203], v[80:83]
	v_mfma_f32_16x16x32_bf16 v[72:75], v[158:161], v[222:225], v[72:75]
	v_mfma_f32_16x16x32_bf16 v[68:71], v[176:179], v[222:225], v[68:71]
	v_mfma_f32_16x16x32_bf16 v[108:111], v[172:175], v[188:191], v[108:111]
	v_mfma_f32_16x16x32_bf16 v[104:107], v[180:183], v[188:191], v[104:107]
	v_mfma_f32_16x16x32_bf16 v[96:99], v[172:175], v[196:199], v[96:99]
	v_mfma_f32_16x16x32_bf16 v[92:95], v[180:183], v[196:199], v[92:95]
	v_mfma_f32_16x16x32_bf16 v[88:91], v[172:175], v[218:221], v[88:91]
	v_mfma_f32_16x16x32_bf16 v[80:83], v[180:183], v[218:221], v[80:83]
	v_mfma_f32_16x16x32_bf16 v[72:75], v[172:175], v[226:229], v[72:75]
	v_mfma_f32_16x16x32_bf16 v[68:71], v[180:183], v[226:229], v[68:71]
	s_barrier
	s_add_i32 s18, s55, s25
	v_lshl_add_u64 v[162:163], v[162:163], 0, s[58:59]
	s_mov_b32 m0, s18
	ds_read_b128 v[184:187], v171 offset:49152
	ds_read_b128 v[188:191], v171 offset:50176
	ds_read_b128 v[192:195], v171 offset:51200
	ds_read_b128 v[196:199], v171 offset:52224
	ds_read_b128 v[200:203], v171 offset:53248
	ds_read_b128 v[218:221], v171 offset:54272
	ds_read_b128 v[222:225], v171 offset:55296
	ds_read_b128 v[226:229], v171 offset:56320
	global_load_lds_dwordx4 v[162:163], off
	s_add_i32 m0, s18, 0x2000
	s_add_u32 s18, s22, 0x80080
	v_lshl_add_u64 v[162:163], v[204:205], 0, s[58:59]
	s_addc_u32 s19, s23, 0
	s_add_i32 s22, s56, s25
	global_load_lds_dwordx4 v[162:163], off
	v_lshl_add_u64 v[162:163], s[18:19], 0, v[66:67]
	s_mov_b32 m0, s22
	s_nop 0
	global_load_lds_dwordx4 v[162:163], off
	v_lshl_add_u64 v[162:163], s[18:19], 0, v[148:149]
	s_add_i32 m0, s22, 0x2000
	s_nop 0
	global_load_lds_dwordx4 v[162:163], off
	v_lshl_add_u64 v[162:163], v[230:231], 0, s[58:59]
	s_mov_b32 m0, s45
	s_nop 0
	global_load_lds_dwordx4 v[162:163], off
	v_lshl_add_u64 v[162:163], v[232:233], 0, s[58:59]
	s_mov_b32 m0, s46
	s_nop 0
	global_load_lds_dwordx4 v[162:163], off
	s_waitcnt vmcnt(8)
	s_waitcnt lgkmcnt(0)
	s_barrier
	s_waitcnt lgkmcnt(0)
	v_mfma_f32_16x16x32_bf16 v[62:65], v[132:135], v[184:187], v[62:65]
	v_mfma_f32_16x16x32_bf16 v[58:61], v[140:143], v[184:187], v[58:61]
	v_mfma_f32_16x16x32_bf16 v[54:57], v[132:135], v[192:195], v[54:57]
	v_mfma_f32_16x16x32_bf16 v[50:53], v[140:143], v[192:195], v[50:53]
	v_mfma_f32_16x16x32_bf16 v[46:49], v[132:135], v[200:203], v[46:49]
	v_mfma_f32_16x16x32_bf16 v[34:37], v[140:143], v[200:203], v[34:37]
	v_mfma_f32_16x16x32_bf16 v[22:25], v[132:135], v[222:225], v[22:25]
	v_mfma_f32_16x16x32_bf16 v[14:17], v[140:143], v[222:225], v[14:17]
	v_mfma_f32_16x16x32_bf16 v[62:65], v[136:139], v[188:191], v[62:65]
	v_mfma_f32_16x16x32_bf16 v[58:61], v[144:147], v[188:191], v[58:61]
	v_mfma_f32_16x16x32_bf16 v[54:57], v[136:139], v[196:199], v[54:57]
	v_mfma_f32_16x16x32_bf16 v[50:53], v[144:147], v[196:199], v[50:53]
	v_mfma_f32_16x16x32_bf16 v[46:49], v[136:139], v[218:221], v[46:49]
	v_mfma_f32_16x16x32_bf16 v[34:37], v[144:147], v[218:221], v[34:37]
	v_mfma_f32_16x16x32_bf16 v[22:25], v[136:139], v[226:229], v[22:25]
	v_mfma_f32_16x16x32_bf16 v[14:17], v[144:147], v[226:229], v[14:17]
	v_mfma_f32_16x16x32_bf16 v[42:45], v[158:161], v[184:187], v[42:45]
	v_mfma_f32_16x16x32_bf16 v[38:41], v[176:179], v[184:187], v[38:41]
	v_mfma_f32_16x16x32_bf16 v[30:33], v[158:161], v[192:195], v[30:33]
	v_mfma_f32_16x16x32_bf16 v[26:29], v[176:179], v[192:195], v[26:29]
	v_mfma_f32_16x16x32_bf16 v[18:21], v[158:161], v[200:203], v[18:21]
	v_mfma_f32_16x16x32_bf16 v[10:13], v[176:179], v[200:203], v[10:13]
	v_mfma_f32_16x16x32_bf16 v[6:9], v[158:161], v[222:225], v[6:9]
	v_mfma_f32_16x16x32_bf16 v[2:5], v[176:179], v[222:225], v[2:5]
	v_mfma_f32_16x16x32_bf16 v[42:45], v[172:175], v[188:191], v[42:45]
	v_mfma_f32_16x16x32_bf16 v[38:41], v[180:183], v[188:191], v[38:41]
	v_mfma_f32_16x16x32_bf16 v[30:33], v[172:175], v[196:199], v[30:33]
	v_mfma_f32_16x16x32_bf16 v[26:29], v[180:183], v[196:199], v[26:29]
	v_mfma_f32_16x16x32_bf16 v[18:21], v[172:175], v[218:221], v[18:21]
	v_mfma_f32_16x16x32_bf16 v[10:13], v[180:183], v[218:221], v[10:13]
	v_mfma_f32_16x16x32_bf16 v[6:9], v[172:175], v[226:229], v[6:9]
	v_mfma_f32_16x16x32_bf16 v[2:5], v[180:183], v[226:229], v[2:5]
	s_barrier
	s_add_i32 s54, s54, 2
	s_add_u32 s52, s52, 0x100
	s_addc_u32 s53, s53, 0
	s_cmp_gt_u32 s54, 29
	s_mov_b64 s[18:19], s[20:21]
	s_cbranch_scc0 .LBB0_1491
	s_and_b64 vcc, exec, s[6:7]
	s_cbranch_vccz .LBB0_1494
	s_barrier

.LBB0_1623:
	s_add_u32 s14, s12, 0xfff80080
	s_addc_u32 s15, s13, -1
	s_add_i32 s49, 0, 0x10000
	s_cmp_eq_u32 s48, 28
	s_cselect_b32 s17, s7, s15
	s_cselect_b32 s16, s44, s14
	v_add_u32_e32 v142, s49, v145
	s_cselect_b32 s15, s5, s47
	s_cselect_b32 s14, s45, s46
	s_add_i32 s52, 0, 0x14000
	ds_read_b128 v[148:151], v142
	ds_read_b128 v[152:155], v142 offset:1024
	ds_read_b128 v[156:159], v142 offset:2048
	ds_read_b128 v[160:163], v142 offset:3072
	v_add_u32_e32 v142, s52, v145
	ds_read_b128 v[168:171], v142
	ds_read_b128 v[172:175], v142 offset:1024
	ds_read_b128 v[176:179], v142 offset:2048
	ds_read_b128 v[180:183], v142 offset:3072
	v_lshl_add_u64 v[142:143], s[12:13], 0, v[138:139]
	s_add_i32 m0, s21, 0xc000
	ds_read_b128 v[184:187], v147
	ds_read_b128 v[188:191], v147 offset:1024
	ds_read_b128 v[192:195], v147 offset:2048
	ds_read_b128 v[196:199], v147 offset:3072
	ds_read_b128 v[200:203], v147 offset:4096
	ds_read_b128 v[218:221], v147 offset:5120
	ds_read_b128 v[222:225], v147 offset:6144
	ds_read_b128 v[226:229], v147 offset:7168
	global_load_lds_dwordx4 v[142:143], off
	v_lshl_add_u64 v[142:143], s[12:13], 0, v[140:141]
	s_add_i32 m0, s21, 0xe000
	s_nop 0
	global_load_lds_dwordx4 v[142:143], off
	s_waitcnt vmcnt(8)
	s_waitcnt lgkmcnt(0)
	s_barrier
	s_waitcnt lgkmcnt(0)
	v_mfma_f32_16x16x32_bf16 v[128:131], v[148:151], v[184:187], v[128:131]
	v_mfma_f32_16x16x32_bf16 v[120:123], v[156:159], v[184:187], v[120:123]
	v_mfma_f32_16x16x32_bf16 v[112:115], v[148:151], v[192:195], v[112:115]
	v_mfma_f32_16x16x32_bf16 v[104:107], v[156:159], v[192:195], v[104:107]
	v_mfma_f32_16x16x32_bf16 v[96:99], v[148:151], v[200:203], v[96:99]
	v_mfma_f32_16x16x32_bf16 v[88:91], v[156:159], v[200:203], v[88:91]
	v_mfma_f32_16x16x32_bf16 v[80:83], v[148:151], v[222:225], v[80:83]
	v_mfma_f32_16x16x32_bf16 v[72:75], v[156:159], v[222:225], v[72:75]
	v_mfma_f32_16x16x32_bf16 v[128:131], v[152:155], v[188:191], v[128:131]
	v_mfma_f32_16x16x32_bf16 v[120:123], v[160:163], v[188:191], v[120:123]
	v_mfma_f32_16x16x32_bf16 v[112:115], v[152:155], v[196:199], v[112:115]
	v_mfma_f32_16x16x32_bf16 v[104:107], v[160:163], v[196:199], v[104:107]
	v_mfma_f32_16x16x32_bf16 v[96:99], v[152:155], v[218:221], v[96:99]
	v_mfma_f32_16x16x32_bf16 v[88:91], v[160:163], v[218:221], v[88:91]
	v_mfma_f32_16x16x32_bf16 v[80:83], v[152:155], v[226:229], v[80:83]
	v_mfma_f32_16x16x32_bf16 v[72:75], v[160:163], v[226:229], v[72:75]
	v_mfma_f32_16x16x32_bf16 v[124:127], v[168:171], v[184:187], v[124:127]
	v_mfma_f32_16x16x32_bf16 v[116:119], v[176:179], v[184:187], v[116:119]
	v_mfma_f32_16x16x32_bf16 v[108:111], v[168:171], v[192:195], v[108:111]
	v_mfma_f32_16x16x32_bf16 v[100:103], v[176:179], v[192:195], v[100:103]
	v_mfma_f32_16x16x32_bf16 v[92:95], v[168:171], v[200:203], v[92:95]
	v_mfma_f32_16x16x32_bf16 v[84:87], v[176:179], v[200:203], v[84:87]
	v_mfma_f32_16x16x32_bf16 v[76:79], v[168:171], v[222:225], v[76:79]
	v_mfma_f32_16x16x32_bf16 v[68:71], v[176:179], v[222:225], v[68:71]
	v_mfma_f32_16x16x32_bf16 v[124:127], v[172:175], v[188:191], v[124:127]
	v_mfma_f32_16x16x32_bf16 v[116:119], v[180:183], v[188:191], v[116:119]
	v_mfma_f32_16x16x32_bf16 v[108:111], v[172:175], v[196:199], v[108:111]
	v_mfma_f32_16x16x32_bf16 v[100:103], v[180:183], v[196:199], v[100:103]
	v_mfma_f32_16x16x32_bf16 v[92:95], v[172:175], v[218:221], v[92:95]
	v_mfma_f32_16x16x32_bf16 v[84:87], v[180:183], v[218:221], v[84:87]
	v_mfma_f32_16x16x32_bf16 v[76:79], v[172:175], v[226:229], v[76:79]
	v_mfma_f32_16x16x32_bf16 v[68:71], v[180:183], v[226:229], v[68:71]
	s_barrier
	s_add_i32 s49, s49, s20
	v_lshl_add_u64 v[142:143], s[14:15], 0, v[66:67]
	s_mov_b32 m0, s49
	ds_read_b128 v[184:187], v147 offset:16384
	ds_read_b128 v[188:191], v147 offset:17408
	ds_read_b128 v[192:195], v147 offset:18432
	ds_read_b128 v[196:199], v147 offset:19456
	ds_read_b128 v[200:203], v147 offset:20480
	ds_read_b128 v[218:221], v147 offset:21504
	ds_read_b128 v[222:225], v147 offset:22528
	ds_read_b128 v[226:229], v147 offset:23552
	global_load_lds_dwordx4 v[142:143], off
	s_add_i32 m0, s49, 0x2000
	s_add_u32 s50, s14, 0x80000
	v_lshl_add_u64 v[164:165], s[14:15], 0, v[132:133]
	s_addc_u32 s51, s15, 0
	s_add_i32 s49, s52, s20
	global_load_lds_dwordx4 v[164:165], off
	v_lshl_add_u64 v[166:167], s[50:51], 0, v[66:67]
	s_mov_b32 m0, s49
	v_lshl_add_u64 v[204:205], s[16:17], 0, v[134:135]
	global_load_lds_dwordx4 v[166:167], off
	v_lshl_add_u64 v[166:167], s[50:51], 0, v[132:133]
	s_add_i32 m0, s49, 0x2000
	s_nop 0
	global_load_lds_dwordx4 v[166:167], off
	v_lshl_add_u64 v[166:167], s[16:17], 0, v[136:137]
	s_mov_b32 m0, s21
	s_nop 0
	global_load_lds_dwordx4 v[166:167], off
	s_mov_b32 m0, s22
	s_nop 0
	global_load_lds_dwordx4 v[204:205], off
	s_waitcnt vmcnt(8)
	s_waitcnt lgkmcnt(0)
	s_barrier
	s_waitcnt lgkmcnt(0)
	v_mfma_f32_16x16x32_bf16 v[62:65], v[148:151], v[184:187], v[62:65]
	v_mfma_f32_16x16x32_bf16 v[54:57], v[156:159], v[184:187], v[54:57]
	v_mfma_f32_16x16x32_bf16 v[46:49], v[148:151], v[192:195], v[46:49]
	v_mfma_f32_16x16x32_bf16 v[38:41], v[156:159], v[192:195], v[38:41]
	v_mfma_f32_16x16x32_bf16 v[30:33], v[148:151], v[200:203], v[30:33]
	v_mfma_f32_16x16x32_bf16 v[22:25], v[156:159], v[200:203], v[22:25]
	v_mfma_f32_16x16x32_bf16 v[14:17], v[148:151], v[222:225], v[14:17]
	v_mfma_f32_16x16x32_bf16 v[6:9], v[156:159], v[222:225], v[6:9]
	v_mfma_f32_16x16x32_bf16 v[62:65], v[152:155], v[188:191], v[62:65]
	v_mfma_f32_16x16x32_bf16 v[54:57], v[160:163], v[188:191], v[54:57]
	v_mfma_f32_16x16x32_bf16 v[46:49], v[152:155], v[196:199], v[46:49]
	v_mfma_f32_16x16x32_bf16 v[38:41], v[160:163], v[196:199], v[38:41]
	v_mfma_f32_16x16x32_bf16 v[30:33], v[152:155], v[218:221], v[30:33]
	v_mfma_f32_16x16x32_bf16 v[22:25], v[160:163], v[218:221], v[22:25]
	v_mfma_f32_16x16x32_bf16 v[14:17], v[152:155], v[226:229], v[14:17]
	v_mfma_f32_16x16x32_bf16 v[6:9], v[160:163], v[226:229], v[6:9]
	v_mfma_f32_16x16x32_bf16 v[58:61], v[168:171], v[184:187], v[58:61]
	v_mfma_f32_16x16x32_bf16 v[50:53], v[176:179], v[184:187], v[50:53]
	v_mfma_f32_16x16x32_bf16 v[42:45], v[168:171], v[192:195], v[42:45]
	v_mfma_f32_16x16x32_bf16 v[34:37], v[176:179], v[192:195], v[34:37]
	v_mfma_f32_16x16x32_bf16 v[26:29], v[168:171], v[200:203], v[26:29]
	v_mfma_f32_16x16x32_bf16 v[18:21], v[176:179], v[200:203], v[18:21]
	v_mfma_f32_16x16x32_bf16 v[10:13], v[168:171], v[222:225], v[10:13]
	v_mfma_f32_16x16x32_bf16 v[2:5], v[176:179], v[222:225], v[2:5]
	v_mfma_f32_16x16x32_bf16 v[58:61], v[172:175], v[188:191], v[58:61]
	v_mfma_f32_16x16x32_bf16 v[50:53], v[180:183], v[188:191], v[50:53]
	v_mfma_f32_16x16x32_bf16 v[42:45], v[172:175], v[196:199], v[42:45]
	v_mfma_f32_16x16x32_bf16 v[34:37], v[180:183], v[196:199], v[34:37]
	v_mfma_f32_16x16x32_bf16 v[26:29], v[172:175], v[218:221], v[26:29]
	v_mfma_f32_16x16x32_bf16 v[18:21], v[180:183], v[218:221], v[18:21]
	v_mfma_f32_16x16x32_bf16 v[10:13], v[172:175], v[226:229], v[10:13]
	v_mfma_f32_16x16x32_bf16 v[2:5], v[180:183], v[226:229], v[2:5]
	s_barrier
	s_add_i32 s49, 0, 0x18000
	s_add_i32 s50, 0, 0x1c000
	v_add_u32_e32 v160, s49, v145
	v_add_u32_e32 v180, s50, v145
	ds_read_b128 v[148:151], v160
	ds_read_b128 v[152:155], v160 offset:1024
	ds_read_b128 v[156:159], v160 offset:2048
	ds_read_b128 v[160:163], v160 offset:3072
	ds_read_b128 v[168:171], v180
	ds_read_b128 v[172:175], v180 offset:1024
	ds_read_b128 v[176:179], v180 offset:2048
	ds_read_b128 v[180:183], v180 offset:3072
	s_add_u32 s16, s16, 0x80000
	s_addc_u32 s17, s17, 0
	s_mov_b32 m0, s23
	v_lshl_add_u64 v[208:209], s[16:17], 0, v[136:137]
	ds_read_b128 v[184:187], v147 offset:32768
	ds_read_b128 v[188:191], v147 offset:33792
	ds_read_b128 v[192:195], v147 offset:34816
	ds_read_b128 v[196:199], v147 offset:35840
	ds_read_b128 v[200:203], v147 offset:36864
	ds_read_b128 v[218:221], v147 offset:37888
	ds_read_b128 v[222:225], v147 offset:38912
	ds_read_b128 v[226:229], v147 offset:39936
	global_load_lds_dwordx4 v[208:209], off
	v_lshl_add_u64 v[208:209], s[16:17], 0, v[134:135]
	s_mov_b32 m0, s28
	s_nop 0
	global_load_lds_dwordx4 v[208:209], off
	s_waitcnt vmcnt(8)
	s_waitcnt lgkmcnt(0)
	s_barrier
	s_waitcnt lgkmcnt(0)
	v_mfma_f32_16x16x32_bf16 v[128:131], v[148:151], v[184:187], v[128:131]
	v_mfma_f32_16x16x32_bf16 v[120:123], v[156:159], v[184:187], v[120:123]
	v_mfma_f32_16x16x32_bf16 v[112:115], v[148:151], v[192:195], v[112:115]
	v_mfma_f32_16x16x32_bf16 v[104:107], v[156:159], v[192:195], v[104:107]
	v_mfma_f32_16x16x32_bf16 v[96:99], v[148:151], v[200:203], v[96:99]
	v_mfma_f32_16x16x32_bf16 v[88:91], v[156:159], v[200:203], v[88:91]
	v_mfma_f32_16x16x32_bf16 v[80:83], v[148:151], v[222:225], v[80:83]
	v_mfma_f32_16x16x32_bf16 v[72:75], v[156:159], v[222:225], v[72:75]
	v_mfma_f32_16x16x32_bf16 v[128:131], v[152:155], v[188:191], v[128:131]
	v_mfma_f32_16x16x32_bf16 v[120:123], v[160:163], v[188:191], v[120:123]
	v_mfma_f32_16x16x32_bf16 v[112:115], v[152:155], v[196:199], v[112:115]
	v_mfma_f32_16x16x32_bf16 v[104:107], v[160:163], v[196:199], v[104:107]
	v_mfma_f32_16x16x32_bf16 v[96:99], v[152:155], v[218:221], v[96:99]
	v_mfma_f32_16x16x32_bf16 v[88:91], v[160:163], v[218:221], v[88:91]
	v_mfma_f32_16x16x32_bf16 v[80:83], v[152:155], v[226:229], v[80:83]
	v_mfma_f32_16x16x32_bf16 v[72:75], v[160:163], v[226:229], v[72:75]
	v_mfma_f32_16x16x32_bf16 v[124:127], v[168:171], v[184:187], v[124:127]
	v_mfma_f32_16x16x32_bf16 v[116:119], v[176:179], v[184:187], v[116:119]
	v_mfma_f32_16x16x32_bf16 v[108:111], v[168:171], v[192:195], v[108:111]
	v_mfma_f32_16x16x32_bf16 v[100:103], v[176:179], v[192:195], v[100:103]
	v_mfma_f32_16x16x32_bf16 v[92:95], v[168:171], v[200:203], v[92:95]
	v_mfma_f32_16x16x32_bf16 v[84:87], v[176:179], v[200:203], v[84:87]
	v_mfma_f32_16x16x32_bf16 v[76:79], v[168:171], v[222:225], v[76:79]
	v_mfma_f32_16x16x32_bf16 v[68:71], v[176:179], v[222:225], v[68:71]
	v_mfma_f32_16x16x32_bf16 v[124:127], v[172:175], v[188:191], v[124:127]
	v_mfma_f32_16x16x32_bf16 v[116:119], v[180:183], v[188:191], v[116:119]
	v_mfma_f32_16x16x32_bf16 v[108:111], v[172:175], v[196:199], v[108:111]
	v_mfma_f32_16x16x32_bf16 v[100:103], v[180:183], v[196:199], v[100:103]
	v_mfma_f32_16x16x32_bf16 v[92:95], v[172:175], v[218:221], v[92:95]
	v_mfma_f32_16x16x32_bf16 v[84:87], v[180:183], v[218:221], v[84:87]
	v_mfma_f32_16x16x32_bf16 v[76:79], v[172:175], v[226:229], v[76:79]
	v_mfma_f32_16x16x32_bf16 v[68:71], v[180:183], v[226:229], v[68:71]
	s_barrier
	s_add_i32 s16, s49, s20
	v_lshl_add_u64 v[142:143], v[142:143], 0, s[54:55]
	s_mov_b32 m0, s16
	ds_read_b128 v[184:187], v147 offset:49152
	ds_read_b128 v[188:191], v147 offset:50176
	ds_read_b128 v[192:195], v147 offset:51200
	ds_read_b128 v[196:199], v147 offset:52224
	ds_read_b128 v[200:203], v147 offset:53248
	ds_read_b128 v[218:221], v147 offset:54272
	ds_read_b128 v[222:225], v147 offset:55296
	ds_read_b128 v[226:229], v147 offset:56320
	global_load_lds_dwordx4 v[142:143], off
	s_add_i32 m0, s16, 0x2000
	s_add_u32 s14, s14, 0x80080
	v_lshl_add_u64 v[142:143], v[164:165], 0, s[54:55]
	s_addc_u32 s15, s15, 0
	s_add_i32 s16, s50, s20
	global_load_lds_dwordx4 v[142:143], off
	v_lshl_add_u64 v[142:143], s[14:15], 0, v[66:67]
	s_mov_b32 m0, s16
	s_nop 0
	global_load_lds_dwordx4 v[142:143], off
	v_lshl_add_u64 v[142:143], s[14:15], 0, v[132:133]
	s_add_i32 m0, s16, 0x2000
	s_nop 0
	global_load_lds_dwordx4 v[142:143], off
	v_lshl_add_u64 v[142:143], v[166:167], 0, s[54:55]
	s_mov_b32 m0, s40
	s_nop 0
	global_load_lds_dwordx4 v[142:143], off
	v_lshl_add_u64 v[142:143], v[204:205], 0, s[54:55]
	s_mov_b32 m0, s41
	s_nop 0
	global_load_lds_dwordx4 v[142:143], off
	s_waitcnt vmcnt(8)
	s_waitcnt lgkmcnt(0)
	s_barrier
	s_waitcnt lgkmcnt(0)
	v_mfma_f32_16x16x32_bf16 v[62:65], v[148:151], v[184:187], v[62:65]
	v_mfma_f32_16x16x32_bf16 v[54:57], v[156:159], v[184:187], v[54:57]
	v_mfma_f32_16x16x32_bf16 v[46:49], v[148:151], v[192:195], v[46:49]
	v_mfma_f32_16x16x32_bf16 v[38:41], v[156:159], v[192:195], v[38:41]
	v_mfma_f32_16x16x32_bf16 v[30:33], v[148:151], v[200:203], v[30:33]
	v_mfma_f32_16x16x32_bf16 v[22:25], v[156:159], v[200:203], v[22:25]
	v_mfma_f32_16x16x32_bf16 v[14:17], v[148:151], v[222:225], v[14:17]
	v_mfma_f32_16x16x32_bf16 v[6:9], v[156:159], v[222:225], v[6:9]
	v_mfma_f32_16x16x32_bf16 v[62:65], v[152:155], v[188:191], v[62:65]
	v_mfma_f32_16x16x32_bf16 v[54:57], v[160:163], v[188:191], v[54:57]
	v_mfma_f32_16x16x32_bf16 v[46:49], v[152:155], v[196:199], v[46:49]
	v_mfma_f32_16x16x32_bf16 v[38:41], v[160:163], v[196:199], v[38:41]
	v_mfma_f32_16x16x32_bf16 v[30:33], v[152:155], v[218:221], v[30:33]
	v_mfma_f32_16x16x32_bf16 v[22:25], v[160:163], v[218:221], v[22:25]
	v_mfma_f32_16x16x32_bf16 v[14:17], v[152:155], v[226:229], v[14:17]
	v_mfma_f32_16x16x32_bf16 v[6:9], v[160:163], v[226:229], v[6:9]
	v_mfma_f32_16x16x32_bf16 v[58:61], v[168:171], v[184:187], v[58:61]
	v_mfma_f32_16x16x32_bf16 v[50:53], v[176:179], v[184:187], v[50:53]
	v_mfma_f32_16x16x32_bf16 v[42:45], v[168:171], v[192:195], v[42:45]
	v_mfma_f32_16x16x32_bf16 v[34:37], v[176:179], v[192:195], v[34:37]
	v_mfma_f32_16x16x32_bf16 v[26:29], v[168:171], v[200:203], v[26:29]
	v_mfma_f32_16x16x32_bf16 v[18:21], v[176:179], v[200:203], v[18:21]
	v_mfma_f32_16x16x32_bf16 v[10:13], v[168:171], v[222:225], v[10:13]
	v_mfma_f32_16x16x32_bf16 v[2:5], v[176:179], v[222:225], v[2:5]
	v_mfma_f32_16x16x32_bf16 v[58:61], v[172:175], v[188:191], v[58:61]
	v_mfma_f32_16x16x32_bf16 v[50:53], v[180:183], v[188:191], v[50:53]
	v_mfma_f32_16x16x32_bf16 v[42:45], v[172:175], v[196:199], v[42:45]
	v_mfma_f32_16x16x32_bf16 v[34:37], v[180:183], v[196:199], v[34:37]
	v_mfma_f32_16x16x32_bf16 v[26:29], v[172:175], v[218:221], v[26:29]
	v_mfma_f32_16x16x32_bf16 v[18:21], v[180:183], v[218:221], v[18:21]
	v_mfma_f32_16x16x32_bf16 v[10:13], v[172:175], v[226:229], v[10:13]
	v_mfma_f32_16x16x32_bf16 v[2:5], v[180:183], v[226:229], v[2:5]
	s_barrier
	s_add_i32 s48, s48, 2
	s_add_u32 s12, s12, 0x100
	s_addc_u32 s13, s13, 0
	s_add_u32 s46, s46, 0x100
	s_addc_u32 s47, s47, 0
	s_cmp_gt_u32 s48, 29
	s_cbranch_scc0 .LBB0_1623
	s_and_b64 vcc, exec, s[2:3]
	s_cbranch_vccz .LBB0_1626
	s_barrier

.LBB0_1764:
	s_add_u32 s20, s18, 0x100
	s_addc_u32 s21, s19, 0
	s_add_i32 s53, 0, 0x10000
	s_cmpk_eq_i32 s52, 0x54
	s_cselect_b32 s37, s3, s21
	s_cselect_b32 s36, s2, s20
	s_cselect_b32 s23, s17, s51
	s_cselect_b32 s22, s16, s50
	s_add_i32 s54, 0, 0x14000
	v_add_u32_e32 v144, s53, v169
	v_add_u32_e32 v162, s54, v169
	ds_read_b128 v[132:135], v144
	ds_read_b128 v[136:139], v144 offset:1024
	ds_read_b128 v[140:143], v144 offset:2048
	ds_read_b128 v[144:147], v144 offset:3072
	ds_read_b128 v[158:161], v162
	ds_read_b128 v[172:175], v162 offset:1024
	ds_read_b128 v[176:179], v162 offset:2048
	ds_read_b128 v[180:183], v162 offset:3072
	v_lshl_add_u64 v[162:163], s[18:19], 0, v[154:155]
	s_add_i32 m0, s39, 0xc000
	ds_read_b128 v[184:187], v171
	ds_read_b128 v[188:191], v171 offset:1024
	ds_read_b128 v[192:195], v171 offset:2048
	ds_read_b128 v[196:199], v171 offset:3072
	ds_read_b128 v[200:203], v171 offset:4096
	ds_read_b128 v[218:221], v171 offset:5120
	ds_read_b128 v[222:225], v171 offset:6144
	ds_read_b128 v[226:229], v171 offset:7168
	global_load_lds_dwordx4 v[162:163], off
	v_lshl_add_u64 v[162:163], s[18:19], 0, v[156:157]
	s_add_i32 m0, s39, 0xe000
	s_nop 0
	global_load_lds_dwordx4 v[162:163], off
	s_waitcnt vmcnt(8)
	s_waitcnt lgkmcnt(0)
	s_barrier
	s_waitcnt lgkmcnt(0)
	v_mfma_f32_16x16x32_bf16 v[128:131], v[132:135], v[184:187], v[128:131]
	v_mfma_f32_16x16x32_bf16 v[124:127], v[140:143], v[184:187], v[124:127]
	v_mfma_f32_16x16x32_bf16 v[120:123], v[132:135], v[192:195], v[120:123]
	v_mfma_f32_16x16x32_bf16 v[116:119], v[140:143], v[192:195], v[116:119]
	v_mfma_f32_16x16x32_bf16 v[112:115], v[132:135], v[200:203], v[112:115]
	v_mfma_f32_16x16x32_bf16 v[100:103], v[140:143], v[200:203], v[100:103]
	v_mfma_f32_16x16x32_bf16 v[84:87], v[132:135], v[222:225], v[84:87]
	v_mfma_f32_16x16x32_bf16 v[76:79], v[140:143], v[222:225], v[76:79]
	v_mfma_f32_16x16x32_bf16 v[128:131], v[136:139], v[188:191], v[128:131]
	v_mfma_f32_16x16x32_bf16 v[124:127], v[144:147], v[188:191], v[124:127]
	v_mfma_f32_16x16x32_bf16 v[120:123], v[136:139], v[196:199], v[120:123]
	v_mfma_f32_16x16x32_bf16 v[116:119], v[144:147], v[196:199], v[116:119]
	v_mfma_f32_16x16x32_bf16 v[112:115], v[136:139], v[218:221], v[112:115]
	v_mfma_f32_16x16x32_bf16 v[100:103], v[144:147], v[218:221], v[100:103]
	v_mfma_f32_16x16x32_bf16 v[84:87], v[136:139], v[226:229], v[84:87]
	v_mfma_f32_16x16x32_bf16 v[76:79], v[144:147], v[226:229], v[76:79]
	v_mfma_f32_16x16x32_bf16 v[108:111], v[158:161], v[184:187], v[108:111]
	v_mfma_f32_16x16x32_bf16 v[104:107], v[176:179], v[184:187], v[104:107]
	v_mfma_f32_16x16x32_bf16 v[96:99], v[158:161], v[192:195], v[96:99]
	v_mfma_f32_16x16x32_bf16 v[92:95], v[176:179], v[192:195], v[92:95]
	v_mfma_f32_16x16x32_bf16 v[88:91], v[158:161], v[200:203], v[88:91]
	v_mfma_f32_16x16x32_bf16 v[80:83], v[176:179], v[200:203], v[80:83]
	v_mfma_f32_16x16x32_bf16 v[72:75], v[158:161], v[222:225], v[72:75]
	v_mfma_f32_16x16x32_bf16 v[68:71], v[176:179], v[222:225], v[68:71]
	v_mfma_f32_16x16x32_bf16 v[108:111], v[172:175], v[188:191], v[108:111]
	v_mfma_f32_16x16x32_bf16 v[104:107], v[180:183], v[188:191], v[104:107]
	v_mfma_f32_16x16x32_bf16 v[96:99], v[172:175], v[196:199], v[96:99]
	v_mfma_f32_16x16x32_bf16 v[92:95], v[180:183], v[196:199], v[92:95]
	v_mfma_f32_16x16x32_bf16 v[88:91], v[172:175], v[218:221], v[88:91]
	v_mfma_f32_16x16x32_bf16 v[80:83], v[180:183], v[218:221], v[80:83]
	v_mfma_f32_16x16x32_bf16 v[72:75], v[172:175], v[226:229], v[72:75]
	v_mfma_f32_16x16x32_bf16 v[68:71], v[180:183], v[226:229], v[68:71]
	s_barrier
	s_add_i32 s18, s53, s25
	v_lshl_add_u64 v[162:163], s[22:23], 0, v[66:67]
	s_mov_b32 m0, s18
	ds_read_b128 v[184:187], v171 offset:16384
	ds_read_b128 v[188:191], v171 offset:17408
	ds_read_b128 v[192:195], v171 offset:18432
	ds_read_b128 v[196:199], v171 offset:19456
	ds_read_b128 v[200:203], v171 offset:20480
	ds_read_b128 v[218:221], v171 offset:21504
	ds_read_b128 v[222:225], v171 offset:22528
	ds_read_b128 v[226:229], v171 offset:23552
	global_load_lds_dwordx4 v[162:163], off
	s_add_i32 m0, s18, 0x2000
	s_add_u32 s18, s22, 0x160000
	v_lshl_add_u64 v[164:165], s[22:23], 0, v[148:149]
	s_addc_u32 s19, s23, 0
	s_add_i32 s53, s54, s25
	global_load_lds_dwordx4 v[164:165], off
	v_lshl_add_u64 v[166:167], s[18:19], 0, v[66:67]
	s_mov_b32 m0, s53
	v_lshl_add_u64 v[204:205], s[36:37], 0, v[148:149]
	global_load_lds_dwordx4 v[166:167], off
	v_lshl_add_u64 v[166:167], s[18:19], 0, v[148:149]
	s_add_i32 m0, s53, 0x2000
	s_nop 0
	global_load_lds_dwordx4 v[166:167], off
	v_lshl_add_u64 v[166:167], s[36:37], 0, v[66:67]
	s_mov_b32 m0, s39
	s_nop 0
	global_load_lds_dwordx4 v[166:167], off
	s_mov_b32 m0, s40
	s_nop 0
	global_load_lds_dwordx4 v[204:205], off
	s_waitcnt vmcnt(8)
	s_waitcnt lgkmcnt(0)
	s_barrier
	s_waitcnt lgkmcnt(0)
	v_mfma_f32_16x16x32_bf16 v[62:65], v[132:135], v[184:187], v[62:65]
	v_mfma_f32_16x16x32_bf16 v[58:61], v[140:143], v[184:187], v[58:61]
	v_mfma_f32_16x16x32_bf16 v[54:57], v[132:135], v[192:195], v[54:57]
	v_mfma_f32_16x16x32_bf16 v[50:53], v[140:143], v[192:195], v[50:53]
	v_mfma_f32_16x16x32_bf16 v[46:49], v[132:135], v[200:203], v[46:49]
	v_mfma_f32_16x16x32_bf16 v[34:37], v[140:143], v[200:203], v[34:37]
	v_mfma_f32_16x16x32_bf16 v[22:25], v[132:135], v[222:225], v[22:25]
	v_mfma_f32_16x16x32_bf16 v[14:17], v[140:143], v[222:225], v[14:17]
	v_mfma_f32_16x16x32_bf16 v[62:65], v[136:139], v[188:191], v[62:65]
	v_mfma_f32_16x16x32_bf16 v[58:61], v[144:147], v[188:191], v[58:61]
	v_mfma_f32_16x16x32_bf16 v[54:57], v[136:139], v[196:199], v[54:57]
	v_mfma_f32_16x16x32_bf16 v[50:53], v[144:147], v[196:199], v[50:53]
	v_mfma_f32_16x16x32_bf16 v[46:49], v[136:139], v[218:221], v[46:49]
	v_mfma_f32_16x16x32_bf16 v[34:37], v[144:147], v[218:221], v[34:37]
	v_mfma_f32_16x16x32_bf16 v[22:25], v[136:139], v[226:229], v[22:25]
	v_mfma_f32_16x16x32_bf16 v[14:17], v[144:147], v[226:229], v[14:17]
	v_mfma_f32_16x16x32_bf16 v[42:45], v[158:161], v[184:187], v[42:45]
	v_mfma_f32_16x16x32_bf16 v[38:41], v[176:179], v[184:187], v[38:41]
	v_mfma_f32_16x16x32_bf16 v[30:33], v[158:161], v[192:195], v[30:33]
	v_mfma_f32_16x16x32_bf16 v[26:29], v[176:179], v[192:195], v[26:29]
	v_mfma_f32_16x16x32_bf16 v[18:21], v[158:161], v[200:203], v[18:21]
	v_mfma_f32_16x16x32_bf16 v[10:13], v[176:179], v[200:203], v[10:13]
	v_mfma_f32_16x16x32_bf16 v[6:9], v[158:161], v[222:225], v[6:9]
	v_mfma_f32_16x16x32_bf16 v[2:5], v[176:179], v[222:225], v[2:5]
	v_mfma_f32_16x16x32_bf16 v[42:45], v[172:175], v[188:191], v[42:45]
	v_mfma_f32_16x16x32_bf16 v[38:41], v[180:183], v[188:191], v[38:41]
	v_mfma_f32_16x16x32_bf16 v[30:33], v[172:175], v[196:199], v[30:33]
	v_mfma_f32_16x16x32_bf16 v[26:29], v[180:183], v[196:199], v[26:29]
	v_mfma_f32_16x16x32_bf16 v[18:21], v[172:175], v[218:221], v[18:21]
	v_mfma_f32_16x16x32_bf16 v[10:13], v[180:183], v[218:221], v[10:13]
	v_mfma_f32_16x16x32_bf16 v[6:9], v[172:175], v[226:229], v[6:9]
	v_mfma_f32_16x16x32_bf16 v[2:5], v[180:183], v[226:229], v[2:5]
	s_barrier
	s_add_i32 s53, 0, 0x18000
	s_add_i32 s54, 0, 0x1c000
	v_add_u32_e32 v144, s53, v169
	v_add_u32_e32 v180, s54, v169
	ds_read_b128 v[132:135], v144
	ds_read_b128 v[136:139], v144 offset:1024
	ds_read_b128 v[140:143], v144 offset:2048
	ds_read_b128 v[144:147], v144 offset:3072
	ds_read_b128 v[158:161], v180
	ds_read_b128 v[172:175], v180 offset:1024
	ds_read_b128 v[176:179], v180 offset:2048
	ds_read_b128 v[180:183], v180 offset:3072
	s_add_u32 s18, s36, 0x160000
	s_addc_u32 s19, s37, 0
	s_mov_b32 m0, s41
	v_lshl_add_u64 v[208:209], s[18:19], 0, v[66:67]
	ds_read_b128 v[184:187], v171 offset:32768
	ds_read_b128 v[188:191], v171 offset:33792
	ds_read_b128 v[192:195], v171 offset:34816
	ds_read_b128 v[196:199], v171 offset:35840
	ds_read_b128 v[200:203], v171 offset:36864
	ds_read_b128 v[218:221], v171 offset:37888
	ds_read_b128 v[222:225], v171 offset:38912
	ds_read_b128 v[226:229], v171 offset:39936
	global_load_lds_dwordx4 v[208:209], off
	v_lshl_add_u64 v[208:209], s[18:19], 0, v[148:149]
	s_mov_b32 m0, s42
	s_nop 0
	global_load_lds_dwordx4 v[208:209], off
	s_waitcnt vmcnt(8)
	s_waitcnt lgkmcnt(0)
	s_barrier
	s_waitcnt lgkmcnt(0)
	v_mfma_f32_16x16x32_bf16 v[128:131], v[132:135], v[184:187], v[128:131]
	v_mfma_f32_16x16x32_bf16 v[124:127], v[140:143], v[184:187], v[124:127]
	v_mfma_f32_16x16x32_bf16 v[120:123], v[132:135], v[192:195], v[120:123]
	v_mfma_f32_16x16x32_bf16 v[116:119], v[140:143], v[192:195], v[116:119]
	v_mfma_f32_16x16x32_bf16 v[112:115], v[132:135], v[200:203], v[112:115]
	v_mfma_f32_16x16x32_bf16 v[100:103], v[140:143], v[200:203], v[100:103]
	v_mfma_f32_16x16x32_bf16 v[84:87], v[132:135], v[222:225], v[84:87]
	v_mfma_f32_16x16x32_bf16 v[76:79], v[140:143], v[222:225], v[76:79]
	v_mfma_f32_16x16x32_bf16 v[128:131], v[136:139], v[188:191], v[128:131]
	v_mfma_f32_16x16x32_bf16 v[124:127], v[144:147], v[188:191], v[124:127]
	v_mfma_f32_16x16x32_bf16 v[120:123], v[136:139], v[196:199], v[120:123]
	v_mfma_f32_16x16x32_bf16 v[116:119], v[144:147], v[196:199], v[116:119]
	v_mfma_f32_16x16x32_bf16 v[112:115], v[136:139], v[218:221], v[112:115]
	v_mfma_f32_16x16x32_bf16 v[100:103], v[144:147], v[218:221], v[100:103]
	v_mfma_f32_16x16x32_bf16 v[84:87], v[136:139], v[226:229], v[84:87]
	v_mfma_f32_16x16x32_bf16 v[76:79], v[144:147], v[226:229], v[76:79]
	v_mfma_f32_16x16x32_bf16 v[108:111], v[158:161], v[184:187], v[108:111]
	v_mfma_f32_16x16x32_bf16 v[104:107], v[176:179], v[184:187], v[104:107]
	v_mfma_f32_16x16x32_bf16 v[96:99], v[158:161], v[192:195], v[96:99]
	v_mfma_f32_16x16x32_bf16 v[92:95], v[176:179], v[192:195], v[92:95]
	v_mfma_f32_16x16x32_bf16 v[88:91], v[158:161], v[200:203], v[88:91]
	v_mfma_f32_16x16x32_bf16 v[80:83], v[176:179], v[200:203], v[80:83]
	v_mfma_f32_16x16x32_bf16 v[72:75], v[158:161], v[222:225], v[72:75]
	v_mfma_f32_16x16x32_bf16 v[68:71], v[176:179], v[222:225], v[68:71]
	v_mfma_f32_16x16x32_bf16 v[108:111], v[172:175], v[188:191], v[108:111]
	v_mfma_f32_16x16x32_bf16 v[104:107], v[180:183], v[188:191], v[104:107]
	v_mfma_f32_16x16x32_bf16 v[96:99], v[172:175], v[196:199], v[96:99]
	v_mfma_f32_16x16x32_bf16 v[92:95], v[180:183], v[196:199], v[92:95]
	v_mfma_f32_16x16x32_bf16 v[88:91], v[172:175], v[218:221], v[88:91]
	v_mfma_f32_16x16x32_bf16 v[80:83], v[180:183], v[218:221], v[80:83]
	v_mfma_f32_16x16x32_bf16 v[72:75], v[172:175], v[226:229], v[72:75]
	v_mfma_f32_16x16x32_bf16 v[68:71], v[180:183], v[226:229], v[68:71]
	s_barrier
	s_add_i32 s18, s53, s25
	v_lshl_add_u64 v[162:163], v[162:163], 0, s[56:57]
	s_mov_b32 m0, s18
	ds_read_b128 v[184:187], v171 offset:49152
	ds_read_b128 v[188:191], v171 offset:50176
	ds_read_b128 v[192:195], v171 offset:51200
	ds_read_b128 v[196:199], v171 offset:52224
	ds_read_b128 v[200:203], v171 offset:53248
	ds_read_b128 v[218:221], v171 offset:54272
	ds_read_b128 v[222:225], v171 offset:55296
	ds_read_b128 v[226:229], v171 offset:56320
	global_load_lds_dwordx4 v[162:163], off
	s_add_i32 m0, s18, 0x2000
	s_add_u32 s18, s22, 0x160080
	v_lshl_add_u64 v[162:163], v[164:165], 0, s[56:57]
	s_addc_u32 s19, s23, 0
	s_add_i32 s22, s54, s25
	global_load_lds_dwordx4 v[162:163], off
	v_lshl_add_u64 v[162:163], s[18:19], 0, v[66:67]
	s_mov_b32 m0, s22
	s_nop 0
	global_load_lds_dwordx4 v[162:163], off
	v_lshl_add_u64 v[162:163], s[18:19], 0, v[148:149]
	s_add_i32 m0, s22, 0x2000
	s_nop 0
	global_load_lds_dwordx4 v[162:163], off
	v_lshl_add_u64 v[162:163], v[166:167], 0, s[56:57]
	s_mov_b32 m0, s43
	s_nop 0
	global_load_lds_dwordx4 v[162:163], off
	v_lshl_add_u64 v[162:163], v[204:205], 0, s[56:57]
	s_mov_b32 m0, s44
	s_nop 0
	global_load_lds_dwordx4 v[162:163], off
	s_waitcnt vmcnt(8)
	s_waitcnt lgkmcnt(0)
	s_barrier
	s_waitcnt lgkmcnt(0)
	v_mfma_f32_16x16x32_bf16 v[62:65], v[132:135], v[184:187], v[62:65]
	v_mfma_f32_16x16x32_bf16 v[58:61], v[140:143], v[184:187], v[58:61]
	v_mfma_f32_16x16x32_bf16 v[54:57], v[132:135], v[192:195], v[54:57]
	v_mfma_f32_16x16x32_bf16 v[50:53], v[140:143], v[192:195], v[50:53]
	v_mfma_f32_16x16x32_bf16 v[46:49], v[132:135], v[200:203], v[46:49]
	v_mfma_f32_16x16x32_bf16 v[34:37], v[140:143], v[200:203], v[34:37]
	v_mfma_f32_16x16x32_bf16 v[22:25], v[132:135], v[222:225], v[22:25]
	v_mfma_f32_16x16x32_bf16 v[14:17], v[140:143], v[222:225], v[14:17]
	v_mfma_f32_16x16x32_bf16 v[62:65], v[136:139], v[188:191], v[62:65]
	v_mfma_f32_16x16x32_bf16 v[58:61], v[144:147], v[188:191], v[58:61]
	v_mfma_f32_16x16x32_bf16 v[54:57], v[136:139], v[196:199], v[54:57]
	v_mfma_f32_16x16x32_bf16 v[50:53], v[144:147], v[196:199], v[50:53]
	v_mfma_f32_16x16x32_bf16 v[46:49], v[136:139], v[218:221], v[46:49]
	v_mfma_f32_16x16x32_bf16 v[34:37], v[144:147], v[218:221], v[34:37]
	v_mfma_f32_16x16x32_bf16 v[22:25], v[136:139], v[226:229], v[22:25]
	v_mfma_f32_16x16x32_bf16 v[14:17], v[144:147], v[226:229], v[14:17]
	v_mfma_f32_16x16x32_bf16 v[42:45], v[158:161], v[184:187], v[42:45]
	v_mfma_f32_16x16x32_bf16 v[38:41], v[176:179], v[184:187], v[38:41]
	v_mfma_f32_16x16x32_bf16 v[30:33], v[158:161], v[192:195], v[30:33]
	v_mfma_f32_16x16x32_bf16 v[26:29], v[176:179], v[192:195], v[26:29]
	v_mfma_f32_16x16x32_bf16 v[18:21], v[158:161], v[200:203], v[18:21]
	v_mfma_f32_16x16x32_bf16 v[10:13], v[176:179], v[200:203], v[10:13]
	v_mfma_f32_16x16x32_bf16 v[6:9], v[158:161], v[222:225], v[6:9]
	v_mfma_f32_16x16x32_bf16 v[2:5], v[176:179], v[222:225], v[2:5]
	v_mfma_f32_16x16x32_bf16 v[42:45], v[172:175], v[188:191], v[42:45]
	v_mfma_f32_16x16x32_bf16 v[38:41], v[180:183], v[188:191], v[38:41]
	v_mfma_f32_16x16x32_bf16 v[30:33], v[172:175], v[196:199], v[30:33]
	v_mfma_f32_16x16x32_bf16 v[26:29], v[180:183], v[196:199], v[26:29]
	v_mfma_f32_16x16x32_bf16 v[18:21], v[172:175], v[218:221], v[18:21]
	v_mfma_f32_16x16x32_bf16 v[10:13], v[180:183], v[218:221], v[10:13]
	v_mfma_f32_16x16x32_bf16 v[6:9], v[172:175], v[226:229], v[6:9]
	v_mfma_f32_16x16x32_bf16 v[2:5], v[180:183], v[226:229], v[2:5]
	s_barrier
	s_add_i32 s52, s52, 2
	s_add_u32 s50, s50, 0x100
	s_addc_u32 s51, s51, 0
	s_cmpk_gt_u32 s52, 0x55
	s_mov_b64 s[18:19], s[20:21]
	s_cbranch_scc0 .LBB0_1764
	s_and_b64 vcc, exec, s[12:13]
	s_cbranch_vccz .LBB0_1767
	s_barrier
